# GEMM K-loops: tile DMAs in SGPR-base form (the 64-bit VALU address adds leave the load segments)
# speedup vs baseline: 1.0086x; 1.0086x over previous
.LBB0_120:
	ds_read_b128 v[130:133], v245
	ds_read_b128 v[134:137], v245 offset:1024
	ds_read_b128 v[138:141], v245 offset:2048
	ds_read_b128 v[142:145], v245 offset:3072
	s_waitcnt vmcnt(0)
	ds_read_b128 v[146:149], v246
	ds_read_b128 v[150:153], v246 offset:1024
	ds_read_b128 v[154:157], v246 offset:2048
	ds_read_b128 v[158:161], v246 offset:3072
	s_add_u32 s16, s6, 0xfffc0080
	s_addc_u32 s17, s7, -1
	s_cmp_eq_u32 s40, 12
	s_cselect_b32 s79, s1, s17
	s_cselect_b32 s78, s2, s16
	s_cselect_b32 s17, s3, s37
	s_cselect_b32 s16, s9, s35
	s_add_i32 m0, s71, 0xc000
	ds_read_b128 v[162:165], v247
	ds_read_b128 v[166:169], v247 offset:1024
	ds_read_b128 v[170:173], v247 offset:2048
	ds_read_b128 v[174:177], v247 offset:3072
	ds_read_b128 v[178:181], v247 offset:4096
	ds_read_b128 v[182:185], v247 offset:5120
	ds_read_b128 v[186:189], v247 offset:6144
	ds_read_b128 v[190:193], v247 offset:7168
	global_load_lds_dwordx4 v226, s[6:7]
	s_add_i32 m0, s71, 0xe000
	s_nop 0
	global_load_lds_dwordx4 v228, s[6:7]
	s_waitcnt vmcnt(8)
	s_waitcnt lgkmcnt(0)
	s_barrier
	s_setprio 1
	s_waitcnt lgkmcnt(0)
	v_mfma_f32_16x16x32_bf16 v[126:129], v[130:133], v[162:165], v[126:129]
	v_mfma_f32_16x16x32_bf16 v[122:125], v[138:141], v[162:165], v[122:125]
	v_mfma_f32_16x16x32_bf16 v[110:113], v[130:133], v[170:173], v[110:113]
	v_mfma_f32_16x16x32_bf16 v[106:109], v[138:141], v[170:173], v[106:109]
	v_mfma_f32_16x16x32_bf16 v[94:97], v[130:133], v[178:181], v[94:97]
	v_mfma_f32_16x16x32_bf16 v[90:93], v[138:141], v[178:181], v[90:93]
	v_mfma_f32_16x16x32_bf16 v[78:81], v[130:133], v[186:189], v[78:81]
	v_mfma_f32_16x16x32_bf16 v[74:77], v[138:141], v[186:189], v[74:77]
	v_mfma_f32_16x16x32_bf16 v[126:129], v[134:137], v[166:169], v[126:129]
	v_mfma_f32_16x16x32_bf16 v[122:125], v[142:145], v[166:169], v[122:125]
	v_mfma_f32_16x16x32_bf16 v[110:113], v[134:137], v[174:177], v[110:113]
	v_mfma_f32_16x16x32_bf16 v[106:109], v[142:145], v[174:177], v[106:109]
	v_mfma_f32_16x16x32_bf16 v[94:97], v[134:137], v[182:185], v[94:97]
	v_mfma_f32_16x16x32_bf16 v[90:93], v[142:145], v[182:185], v[90:93]
	v_mfma_f32_16x16x32_bf16 v[78:81], v[134:137], v[190:193], v[78:81]
	v_mfma_f32_16x16x32_bf16 v[74:77], v[142:145], v[190:193], v[74:77]
	s_setprio 0
	s_setprio 1
	v_mfma_f32_16x16x32_bf16 v[118:121], v[146:149], v[162:165], v[118:121]
	v_mfma_f32_16x16x32_bf16 v[114:117], v[154:157], v[162:165], v[114:117]
	v_mfma_f32_16x16x32_bf16 v[102:105], v[146:149], v[170:173], v[102:105]
	v_mfma_f32_16x16x32_bf16 v[98:101], v[154:157], v[170:173], v[98:101]
	v_mfma_f32_16x16x32_bf16 v[86:89], v[146:149], v[178:181], v[86:89]
	v_mfma_f32_16x16x32_bf16 v[82:85], v[154:157], v[178:181], v[82:85]
	v_mfma_f32_16x16x32_bf16 v[70:73], v[146:149], v[186:189], v[70:73]
	v_mfma_f32_16x16x32_bf16 v[66:69], v[154:157], v[186:189], v[66:69]
	v_mfma_f32_16x16x32_bf16 v[118:121], v[150:153], v[166:169], v[118:121]
	v_mfma_f32_16x16x32_bf16 v[114:117], v[158:161], v[166:169], v[114:117]
	v_mfma_f32_16x16x32_bf16 v[102:105], v[150:153], v[174:177], v[102:105]
	v_mfma_f32_16x16x32_bf16 v[98:101], v[158:161], v[174:177], v[98:101]
	v_mfma_f32_16x16x32_bf16 v[86:89], v[150:153], v[182:185], v[86:89]
	v_mfma_f32_16x16x32_bf16 v[82:85], v[158:161], v[182:185], v[82:85]
	v_mfma_f32_16x16x32_bf16 v[70:73], v[150:153], v[190:193], v[70:73]
	v_mfma_f32_16x16x32_bf16 v[66:69], v[158:161], v[190:193], v[66:69]
	s_setprio 0
	s_barrier
	s_add_i32 s41, s12, s39
	s_mov_b32 m0, s41
	ds_read_b128 v[162:165], v247 offset:16384
	ds_read_b128 v[166:169], v247 offset:17408
	ds_read_b128 v[170:173], v247 offset:18432
	ds_read_b128 v[174:177], v247 offset:19456
	ds_read_b128 v[178:181], v247 offset:20480
	ds_read_b128 v[182:185], v247 offset:21504
	ds_read_b128 v[186:189], v247 offset:22528
	ds_read_b128 v[190:193], v247 offset:23552
	global_load_lds_dwordx4 v212, s[16:17]
	s_add_i32 m0, s41, 0x2000
	s_add_u32 s42, s16, 0x40000
	s_addc_u32 s43, s17, 0
	s_add_i32 s41, s13, s39
	global_load_lds_dwordx4 v216, s[16:17]
	s_mov_b32 m0, s41
	s_nop 0
	global_load_lds_dwordx4 v212, s[42:43]
	s_add_i32 m0, s41, 0x2000
	s_nop 0
	global_load_lds_dwordx4 v216, s[42:43]
	s_mov_b32 m0, s71
	s_nop 0
	global_load_lds_dwordx4 v210, s[78:79]
	s_mov_b32 m0, s20
	s_nop 0
	global_load_lds_dwordx4 v214, s[78:79]
	s_waitcnt vmcnt(8)
	s_waitcnt lgkmcnt(0)
	s_barrier
	s_setprio 1
	s_waitcnt lgkmcnt(0)
	v_mfma_f32_16x16x32_bf16 v[62:65], v[130:133], v[162:165], v[62:65]
	v_mfma_f32_16x16x32_bf16 v[58:61], v[138:141], v[162:165], v[58:61]
	v_mfma_f32_16x16x32_bf16 v[46:49], v[130:133], v[170:173], v[46:49]
	v_mfma_f32_16x16x32_bf16 v[42:45], v[138:141], v[170:173], v[42:45]
	v_mfma_f32_16x16x32_bf16 v[30:33], v[130:133], v[178:181], v[30:33]
	v_mfma_f32_16x16x32_bf16 v[26:29], v[138:141], v[178:181], v[26:29]
	v_mfma_f32_16x16x32_bf16 v[14:17], v[130:133], v[186:189], v[14:17]
	v_mfma_f32_16x16x32_bf16 v[10:13], v[138:141], v[186:189], v[10:13]
	v_mfma_f32_16x16x32_bf16 v[62:65], v[134:137], v[166:169], v[62:65]
	v_mfma_f32_16x16x32_bf16 v[58:61], v[142:145], v[166:169], v[58:61]
	v_mfma_f32_16x16x32_bf16 v[46:49], v[134:137], v[174:177], v[46:49]
	v_mfma_f32_16x16x32_bf16 v[42:45], v[142:145], v[174:177], v[42:45]
	v_mfma_f32_16x16x32_bf16 v[30:33], v[134:137], v[182:185], v[30:33]
	v_mfma_f32_16x16x32_bf16 v[26:29], v[142:145], v[182:185], v[26:29]
	v_mfma_f32_16x16x32_bf16 v[14:17], v[134:137], v[190:193], v[14:17]
	v_mfma_f32_16x16x32_bf16 v[10:13], v[142:145], v[190:193], v[10:13]
	s_setprio 0
	s_setprio 1
	v_mfma_f32_16x16x32_bf16 v[54:57], v[146:149], v[162:165], v[54:57]
	v_mfma_f32_16x16x32_bf16 v[50:53], v[154:157], v[162:165], v[50:53]
	v_mfma_f32_16x16x32_bf16 v[38:41], v[146:149], v[170:173], v[38:41]
	v_mfma_f32_16x16x32_bf16 v[34:37], v[154:157], v[170:173], v[34:37]
	v_mfma_f32_16x16x32_bf16 v[22:25], v[146:149], v[178:181], v[22:25]
	v_mfma_f32_16x16x32_bf16 v[18:21], v[154:157], v[178:181], v[18:21]
	v_mfma_f32_16x16x32_bf16 v[6:9], v[146:149], v[186:189], v[6:9]
	v_mfma_f32_16x16x32_bf16 v[2:5], v[154:157], v[186:189], v[2:5]
	v_mfma_f32_16x16x32_bf16 v[54:57], v[150:153], v[166:169], v[54:57]
	v_mfma_f32_16x16x32_bf16 v[50:53], v[158:161], v[166:169], v[50:53]
	v_mfma_f32_16x16x32_bf16 v[38:41], v[150:153], v[174:177], v[38:41]
	v_mfma_f32_16x16x32_bf16 v[34:37], v[158:161], v[174:177], v[34:37]
	v_mfma_f32_16x16x32_bf16 v[22:25], v[150:153], v[182:185], v[22:25]
	v_mfma_f32_16x16x32_bf16 v[18:21], v[158:161], v[182:185], v[18:21]
	v_mfma_f32_16x16x32_bf16 v[6:9], v[150:153], v[190:193], v[6:9]
	v_mfma_f32_16x16x32_bf16 v[2:5], v[158:161], v[190:193], v[2:5]
	s_setprio 0
	s_barrier
	s_add_i32 s41, 0, 0x18000
	s_add_i32 s44, 0, 0x1c000
	v_add_u32_e32 v142, s41, v223
	v_add_u32_e32 v158, s44, v223
	ds_read_b128 v[130:133], v142
	ds_read_b128 v[134:137], v142 offset:1024
	ds_read_b128 v[138:141], v142 offset:2048
	ds_read_b128 v[142:145], v142 offset:3072
	ds_read_b128 v[146:149], v158
	ds_read_b128 v[150:153], v158 offset:1024
	ds_read_b128 v[154:157], v158 offset:2048
	ds_read_b128 v[158:161], v158 offset:3072
	s_add_u32 s42, s78, 0x40000
	s_addc_u32 s43, s79, 0
	s_mov_b32 m0, s21
	ds_read_b128 v[162:165], v247 offset:32768
	ds_read_b128 v[166:169], v247 offset:33792
	ds_read_b128 v[170:173], v247 offset:34816
	ds_read_b128 v[174:177], v247 offset:35840
	ds_read_b128 v[178:181], v247 offset:36864
	ds_read_b128 v[182:185], v247 offset:37888
	ds_read_b128 v[186:189], v247 offset:38912
	ds_read_b128 v[190:193], v247 offset:39936
	global_load_lds_dwordx4 v210, s[42:43]
	s_mov_b32 m0, s22
	s_nop 0
	global_load_lds_dwordx4 v214, s[42:43]
	s_waitcnt vmcnt(8)
	s_waitcnt lgkmcnt(0)
	s_barrier
	s_setprio 1
	s_waitcnt lgkmcnt(0)
	v_mfma_f32_16x16x32_bf16 v[126:129], v[130:133], v[162:165], v[126:129]
	v_mfma_f32_16x16x32_bf16 v[122:125], v[138:141], v[162:165], v[122:125]
	v_mfma_f32_16x16x32_bf16 v[110:113], v[130:133], v[170:173], v[110:113]
	v_mfma_f32_16x16x32_bf16 v[106:109], v[138:141], v[170:173], v[106:109]
	v_mfma_f32_16x16x32_bf16 v[94:97], v[130:133], v[178:181], v[94:97]
	v_mfma_f32_16x16x32_bf16 v[90:93], v[138:141], v[178:181], v[90:93]
	v_mfma_f32_16x16x32_bf16 v[78:81], v[130:133], v[186:189], v[78:81]
	v_mfma_f32_16x16x32_bf16 v[74:77], v[138:141], v[186:189], v[74:77]
	v_mfma_f32_16x16x32_bf16 v[126:129], v[134:137], v[166:169], v[126:129]
	v_mfma_f32_16x16x32_bf16 v[122:125], v[142:145], v[166:169], v[122:125]
	v_mfma_f32_16x16x32_bf16 v[110:113], v[134:137], v[174:177], v[110:113]
	v_mfma_f32_16x16x32_bf16 v[106:109], v[142:145], v[174:177], v[106:109]
	v_mfma_f32_16x16x32_bf16 v[94:97], v[134:137], v[182:185], v[94:97]
	v_mfma_f32_16x16x32_bf16 v[90:93], v[142:145], v[182:185], v[90:93]
	v_mfma_f32_16x16x32_bf16 v[78:81], v[134:137], v[190:193], v[78:81]
	v_mfma_f32_16x16x32_bf16 v[74:77], v[142:145], v[190:193], v[74:77]
	s_setprio 0
	s_setprio 1
	v_mfma_f32_16x16x32_bf16 v[118:121], v[146:149], v[162:165], v[118:121]
	v_mfma_f32_16x16x32_bf16 v[114:117], v[154:157], v[162:165], v[114:117]
	v_mfma_f32_16x16x32_bf16 v[102:105], v[146:149], v[170:173], v[102:105]
	v_mfma_f32_16x16x32_bf16 v[98:101], v[154:157], v[170:173], v[98:101]
	v_mfma_f32_16x16x32_bf16 v[86:89], v[146:149], v[178:181], v[86:89]
	v_mfma_f32_16x16x32_bf16 v[82:85], v[154:157], v[178:181], v[82:85]
	v_mfma_f32_16x16x32_bf16 v[70:73], v[146:149], v[186:189], v[70:73]
	v_mfma_f32_16x16x32_bf16 v[66:69], v[154:157], v[186:189], v[66:69]
	v_mfma_f32_16x16x32_bf16 v[118:121], v[150:153], v[166:169], v[118:121]
	v_mfma_f32_16x16x32_bf16 v[114:117], v[158:161], v[166:169], v[114:117]
	v_mfma_f32_16x16x32_bf16 v[102:105], v[150:153], v[174:177], v[102:105]
	v_mfma_f32_16x16x32_bf16 v[98:101], v[158:161], v[174:177], v[98:101]
	v_mfma_f32_16x16x32_bf16 v[86:89], v[150:153], v[182:185], v[86:89]
	v_mfma_f32_16x16x32_bf16 v[82:85], v[158:161], v[182:185], v[82:85]
	v_mfma_f32_16x16x32_bf16 v[70:73], v[150:153], v[190:193], v[70:73]
	v_mfma_f32_16x16x32_bf16 v[66:69], v[158:161], v[190:193], v[66:69]
	s_setprio 0
	s_barrier
	s_add_i32 s41, s41, s39
	s_add_i32 m0, s41, 0xffffff80
	ds_read_b128 v[162:165], v247 offset:49152
	ds_read_b128 v[166:169], v247 offset:50176
	ds_read_b128 v[170:173], v247 offset:51200
	ds_read_b128 v[174:177], v247 offset:52224
	ds_read_b128 v[178:181], v247 offset:53248
	ds_read_b128 v[182:185], v247 offset:54272
	ds_read_b128 v[186:189], v247 offset:55296
	ds_read_b128 v[190:193], v247 offset:56320
	global_load_lds_dwordx4 v212, s[16:17] offset:128
	s_add_i32 m0, s41, 0x1f80
	s_add_i32 s41, s44, s39
	global_load_lds_dwordx4 v216, s[16:17] offset:128
	s_add_u32 s16, s16, 0x40080
	s_addc_u32 s17, s17, 0
	s_mov_b32 m0, s41
	s_nop 0
	global_load_lds_dwordx4 v212, s[16:17]
	s_add_i32 m0, s41, 0x2000
	s_nop 0
	global_load_lds_dwordx4 v216, s[16:17]
	s_add_i32 m0, s14, 0xffffff80
	s_nop 0
	global_load_lds_dwordx4 v210, s[78:79] offset:128
	s_add_i32 m0, s15, 0xffffff80
	s_nop 0
	global_load_lds_dwordx4 v214, s[78:79] offset:128
	s_waitcnt vmcnt(8)
	s_waitcnt lgkmcnt(0)
	s_barrier
	s_setprio 1
	s_waitcnt lgkmcnt(0)
	v_mfma_f32_16x16x32_bf16 v[62:65], v[130:133], v[162:165], v[62:65]
	v_mfma_f32_16x16x32_bf16 v[58:61], v[138:141], v[162:165], v[58:61]
	v_mfma_f32_16x16x32_bf16 v[46:49], v[130:133], v[170:173], v[46:49]
	v_mfma_f32_16x16x32_bf16 v[42:45], v[138:141], v[170:173], v[42:45]
	v_mfma_f32_16x16x32_bf16 v[30:33], v[130:133], v[178:181], v[30:33]
	v_mfma_f32_16x16x32_bf16 v[26:29], v[138:141], v[178:181], v[26:29]
	v_mfma_f32_16x16x32_bf16 v[14:17], v[130:133], v[186:189], v[14:17]
	v_mfma_f32_16x16x32_bf16 v[10:13], v[138:141], v[186:189], v[10:13]
	v_mfma_f32_16x16x32_bf16 v[62:65], v[134:137], v[166:169], v[62:65]
	v_mfma_f32_16x16x32_bf16 v[58:61], v[142:145], v[166:169], v[58:61]
	v_mfma_f32_16x16x32_bf16 v[46:49], v[134:137], v[174:177], v[46:49]
	v_mfma_f32_16x16x32_bf16 v[42:45], v[142:145], v[174:177], v[42:45]
	v_mfma_f32_16x16x32_bf16 v[30:33], v[134:137], v[182:185], v[30:33]
	v_mfma_f32_16x16x32_bf16 v[26:29], v[142:145], v[182:185], v[26:29]
	v_mfma_f32_16x16x32_bf16 v[14:17], v[134:137], v[190:193], v[14:17]
	v_mfma_f32_16x16x32_bf16 v[10:13], v[142:145], v[190:193], v[10:13]
	s_setprio 0
	s_setprio 1
	v_mfma_f32_16x16x32_bf16 v[54:57], v[146:149], v[162:165], v[54:57]
	v_mfma_f32_16x16x32_bf16 v[50:53], v[154:157], v[162:165], v[50:53]
	v_mfma_f32_16x16x32_bf16 v[38:41], v[146:149], v[170:173], v[38:41]
	v_mfma_f32_16x16x32_bf16 v[34:37], v[154:157], v[170:173], v[34:37]
	v_mfma_f32_16x16x32_bf16 v[22:25], v[146:149], v[178:181], v[22:25]
	v_mfma_f32_16x16x32_bf16 v[18:21], v[154:157], v[178:181], v[18:21]
	v_mfma_f32_16x16x32_bf16 v[6:9], v[146:149], v[186:189], v[6:9]
	v_mfma_f32_16x16x32_bf16 v[2:5], v[154:157], v[186:189], v[2:5]
	v_mfma_f32_16x16x32_bf16 v[54:57], v[150:153], v[166:169], v[54:57]
	v_mfma_f32_16x16x32_bf16 v[50:53], v[158:161], v[166:169], v[50:53]
	v_mfma_f32_16x16x32_bf16 v[38:41], v[150:153], v[174:177], v[38:41]
	v_mfma_f32_16x16x32_bf16 v[34:37], v[158:161], v[174:177], v[34:37]
	v_mfma_f32_16x16x32_bf16 v[22:25], v[150:153], v[182:185], v[22:25]
	v_mfma_f32_16x16x32_bf16 v[18:21], v[158:161], v[182:185], v[18:21]
	v_mfma_f32_16x16x32_bf16 v[6:9], v[150:153], v[190:193], v[6:9]
	v_mfma_f32_16x16x32_bf16 v[2:5], v[158:161], v[190:193], v[2:5]
	s_setprio 0
	s_barrier
	s_add_i32 s40, s40, 2
	s_add_u32 s6, s6, 0x100
	s_addc_u32 s7, s7, 0
	s_add_u32 s35, s35, 0x100
	s_addc_u32 s37, s37, 0
	s_cmp_gt_u32 s40, 13
	s_cbranch_scc0 .LBB0_120
	s_and_b64 vcc, exec, s[48:49]
	s_cbranch_vccz .LBB0_123
	s_barrier

.LBB0_518:
	ds_read_b128 v[148:151], v143
	ds_read_b128 v[152:155], v143 offset:1024
	ds_read_b128 v[158:161], v143 offset:2048
	ds_read_b128 v[162:165], v143 offset:3072
	ds_read_b128 v[166:169], v144
	ds_read_b128 v[170:173], v144 offset:1024
	ds_read_b128 v[174:177], v144 offset:2048
	ds_read_b128 v[178:181], v144 offset:3072
	s_add_u32 s16, s8, s10
	s_addc_u32 s17, s9, s11
	s_add_u32 s16, s16, 0x1000100
	s_addc_u32 s17, s17, 0
	s_add_u32 s44, s30, s10
	s_addc_u32 s45, s31, s11
	s_cmpk_eq_i32 s10, 0x700
	s_cselect_b32 s29, s7, s17
	s_cselect_b32 s28, s6, s16
	s_cselect_b32 s17, s5, s45
	s_cselect_b32 s16, s4, s44
	s_mov_b32 m0, s34
	v_lshl_add_u64 v[214:215], v[138:139], 0, s[10:11]
	ds_read_b128 v[182:185], v145
	ds_read_b128 v[186:189], v145 offset:1024
	ds_read_b128 v[190:193], v145 offset:2048
	ds_read_b128 v[194:197], v145 offset:3072
	ds_read_b128 v[198:201], v145 offset:4096
	ds_read_b128 v[202:205], v145 offset:5120
	ds_read_b128 v[206:209], v145 offset:6144
	ds_read_b128 v[210:213], v145 offset:7168
	global_load_lds_dwordx4 v[214:215], off
	v_lshl_add_u64 v[214:215], v[140:141], 0, s[10:11]
	s_mov_b32 m0, s35
	s_nop 0
	global_load_lds_dwordx4 v[214:215], off
	s_waitcnt vmcnt(8)
	s_waitcnt lgkmcnt(0)
	s_barrier
	s_setprio 1
	s_waitcnt lgkmcnt(0)
	v_mfma_f32_16x16x32_bf16 v[126:129], v[148:151], v[182:185], v[126:129]
	v_mfma_f32_16x16x32_bf16 v[122:125], v[158:161], v[182:185], v[122:125]
	v_mfma_f32_16x16x32_bf16 v[110:113], v[148:151], v[190:193], v[110:113]
	v_mfma_f32_16x16x32_bf16 v[106:109], v[158:161], v[190:193], v[106:109]
	v_mfma_f32_16x16x32_bf16 v[94:97], v[148:151], v[198:201], v[94:97]
	v_mfma_f32_16x16x32_bf16 v[90:93], v[158:161], v[198:201], v[90:93]
	v_mfma_f32_16x16x32_bf16 v[78:81], v[148:151], v[206:209], v[78:81]
	v_mfma_f32_16x16x32_bf16 v[74:77], v[158:161], v[206:209], v[74:77]
	v_mfma_f32_16x16x32_bf16 v[126:129], v[152:155], v[186:189], v[126:129]
	v_mfma_f32_16x16x32_bf16 v[122:125], v[162:165], v[186:189], v[122:125]
	v_mfma_f32_16x16x32_bf16 v[110:113], v[152:155], v[194:197], v[110:113]
	v_mfma_f32_16x16x32_bf16 v[106:109], v[162:165], v[194:197], v[106:109]
	v_mfma_f32_16x16x32_bf16 v[94:97], v[152:155], v[202:205], v[94:97]
	v_mfma_f32_16x16x32_bf16 v[90:93], v[162:165], v[202:205], v[90:93]
	v_mfma_f32_16x16x32_bf16 v[78:81], v[152:155], v[210:213], v[78:81]
	v_mfma_f32_16x16x32_bf16 v[74:77], v[162:165], v[210:213], v[74:77]
	s_setprio 0
	s_setprio 1
	v_mfma_f32_16x16x32_bf16 v[118:121], v[166:169], v[182:185], v[118:121]
	v_mfma_f32_16x16x32_bf16 v[114:117], v[174:177], v[182:185], v[114:117]
	v_mfma_f32_16x16x32_bf16 v[102:105], v[166:169], v[190:193], v[102:105]
	v_mfma_f32_16x16x32_bf16 v[98:101], v[174:177], v[190:193], v[98:101]
	v_mfma_f32_16x16x32_bf16 v[86:89], v[166:169], v[198:201], v[86:89]
	v_mfma_f32_16x16x32_bf16 v[82:85], v[174:177], v[198:201], v[82:85]
	v_mfma_f32_16x16x32_bf16 v[70:73], v[166:169], v[206:209], v[70:73]
	v_mfma_f32_16x16x32_bf16 v[66:69], v[174:177], v[206:209], v[66:69]
	v_mfma_f32_16x16x32_bf16 v[118:121], v[170:173], v[186:189], v[118:121]
	v_mfma_f32_16x16x32_bf16 v[114:117], v[178:181], v[186:189], v[114:117]
	v_mfma_f32_16x16x32_bf16 v[102:105], v[170:173], v[194:197], v[102:105]
	v_mfma_f32_16x16x32_bf16 v[98:101], v[178:181], v[194:197], v[98:101]
	v_mfma_f32_16x16x32_bf16 v[86:89], v[170:173], v[202:205], v[86:89]
	v_mfma_f32_16x16x32_bf16 v[82:85], v[178:181], v[202:205], v[82:85]
	v_mfma_f32_16x16x32_bf16 v[70:73], v[170:173], v[210:213], v[70:73]
	v_mfma_f32_16x16x32_bf16 v[66:69], v[178:181], v[210:213], v[66:69]
	s_setprio 0
	s_barrier
	s_mov_b32 m0, s36
	v_lshl_add_u64 v[214:215], s[16:17], 0, v[132:133]
	s_add_u32 s44, s16, 0x40000
	ds_read_b128 v[182:185], v145 offset:16384
	ds_read_b128 v[186:189], v145 offset:17408
	ds_read_b128 v[190:193], v145 offset:18432
	ds_read_b128 v[194:197], v145 offset:19456
	ds_read_b128 v[198:201], v145 offset:20480
	ds_read_b128 v[202:205], v145 offset:21504
	ds_read_b128 v[206:209], v145 offset:22528
	ds_read_b128 v[210:213], v145 offset:23552
	global_load_lds_dwordx4 v132, s[16:17]
	v_lshl_add_u64 v[216:217], s[16:17], 0, v[136:137]
	s_mov_b32 m0, s37
	s_addc_u32 s45, s17, 0
	global_load_lds_dwordx4 v136, s[16:17]
	s_mov_b32 m0, s38
	v_lshl_add_u64 v[220:221], s[28:29], 0, v[134:135]
	global_load_lds_dwordx4 v132, s[44:45]
	s_mov_b32 m0, s39
	s_nop 0
	global_load_lds_dwordx4 v136, s[44:45]
	v_lshl_add_u64 v[218:219], s[28:29], 0, v[130:131]
	s_mov_b32 m0, s1
	s_nop 0
	global_load_lds_dwordx4 v130, s[28:29]
	s_mov_b32 m0, s15
	s_nop 0
	global_load_lds_dwordx4 v134, s[28:29]
	s_waitcnt vmcnt(8)
	s_waitcnt lgkmcnt(0)
	s_barrier
	s_setprio 1
	s_waitcnt lgkmcnt(0)
	v_mfma_f32_16x16x32_bf16 v[62:65], v[148:151], v[182:185], v[62:65]
	v_mfma_f32_16x16x32_bf16 v[58:61], v[158:161], v[182:185], v[58:61]
	v_mfma_f32_16x16x32_bf16 v[46:49], v[148:151], v[190:193], v[46:49]
	v_mfma_f32_16x16x32_bf16 v[42:45], v[158:161], v[190:193], v[42:45]
	v_mfma_f32_16x16x32_bf16 v[30:33], v[148:151], v[198:201], v[30:33]
	v_mfma_f32_16x16x32_bf16 v[26:29], v[158:161], v[198:201], v[26:29]
	v_mfma_f32_16x16x32_bf16 v[14:17], v[148:151], v[206:209], v[14:17]
	v_mfma_f32_16x16x32_bf16 v[10:13], v[158:161], v[206:209], v[10:13]
	v_mfma_f32_16x16x32_bf16 v[62:65], v[152:155], v[186:189], v[62:65]
	v_mfma_f32_16x16x32_bf16 v[58:61], v[162:165], v[186:189], v[58:61]
	v_mfma_f32_16x16x32_bf16 v[46:49], v[152:155], v[194:197], v[46:49]
	v_mfma_f32_16x16x32_bf16 v[42:45], v[162:165], v[194:197], v[42:45]
	v_mfma_f32_16x16x32_bf16 v[30:33], v[152:155], v[202:205], v[30:33]
	v_mfma_f32_16x16x32_bf16 v[26:29], v[162:165], v[202:205], v[26:29]
	v_mfma_f32_16x16x32_bf16 v[14:17], v[152:155], v[210:213], v[14:17]
	v_mfma_f32_16x16x32_bf16 v[10:13], v[162:165], v[210:213], v[10:13]
	s_setprio 0
	s_setprio 1
	v_mfma_f32_16x16x32_bf16 v[54:57], v[166:169], v[182:185], v[54:57]
	v_mfma_f32_16x16x32_bf16 v[50:53], v[174:177], v[182:185], v[50:53]
	v_mfma_f32_16x16x32_bf16 v[38:41], v[166:169], v[190:193], v[38:41]
	v_mfma_f32_16x16x32_bf16 v[34:37], v[174:177], v[190:193], v[34:37]
	v_mfma_f32_16x16x32_bf16 v[22:25], v[166:169], v[198:201], v[22:25]
	v_mfma_f32_16x16x32_bf16 v[18:21], v[174:177], v[198:201], v[18:21]
	v_mfma_f32_16x16x32_bf16 v[6:9], v[166:169], v[206:209], v[6:9]
	v_mfma_f32_16x16x32_bf16 v[2:5], v[174:177], v[206:209], v[2:5]
	v_mfma_f32_16x16x32_bf16 v[54:57], v[170:173], v[186:189], v[54:57]
	v_mfma_f32_16x16x32_bf16 v[50:53], v[178:181], v[186:189], v[50:53]
	v_mfma_f32_16x16x32_bf16 v[38:41], v[170:173], v[194:197], v[38:41]
	v_mfma_f32_16x16x32_bf16 v[34:37], v[178:181], v[194:197], v[34:37]
	v_mfma_f32_16x16x32_bf16 v[22:25], v[170:173], v[202:205], v[22:25]
	v_mfma_f32_16x16x32_bf16 v[18:21], v[178:181], v[202:205], v[18:21]
	v_mfma_f32_16x16x32_bf16 v[6:9], v[170:173], v[210:213], v[6:9]
	v_mfma_f32_16x16x32_bf16 v[2:5], v[178:181], v[210:213], v[2:5]
	s_setprio 0
	s_barrier
	ds_read_b128 v[148:151], v146
	ds_read_b128 v[152:155], v146 offset:1024
	ds_read_b128 v[158:161], v146 offset:2048
	ds_read_b128 v[162:165], v146 offset:3072
	ds_read_b128 v[166:169], v147
	ds_read_b128 v[170:173], v147 offset:1024
	ds_read_b128 v[174:177], v147 offset:2048
	ds_read_b128 v[178:181], v147 offset:3072
	s_add_u32 s28, s28, 0x40000
	s_addc_u32 s29, s29, 0
	s_mov_b32 m0, s20
	ds_read_b128 v[182:185], v145 offset:32768
	ds_read_b128 v[186:189], v145 offset:33792
	ds_read_b128 v[190:193], v145 offset:34816
	ds_read_b128 v[194:197], v145 offset:35840
	ds_read_b128 v[198:201], v145 offset:36864
	ds_read_b128 v[202:205], v145 offset:37888
	ds_read_b128 v[206:209], v145 offset:38912
	ds_read_b128 v[210:213], v145 offset:39936
	global_load_lds_dwordx4 v130, s[28:29]
	s_mov_b32 m0, s21
	s_nop 0
	global_load_lds_dwordx4 v134, s[28:29]
	s_waitcnt vmcnt(8)
	s_waitcnt lgkmcnt(0)
	s_barrier
	s_setprio 1
	s_waitcnt lgkmcnt(0)
	v_mfma_f32_16x16x32_bf16 v[126:129], v[148:151], v[182:185], v[126:129]
	v_mfma_f32_16x16x32_bf16 v[122:125], v[158:161], v[182:185], v[122:125]
	v_mfma_f32_16x16x32_bf16 v[110:113], v[148:151], v[190:193], v[110:113]
	v_mfma_f32_16x16x32_bf16 v[106:109], v[158:161], v[190:193], v[106:109]
	v_mfma_f32_16x16x32_bf16 v[94:97], v[148:151], v[198:201], v[94:97]
	v_mfma_f32_16x16x32_bf16 v[90:93], v[158:161], v[198:201], v[90:93]
	v_mfma_f32_16x16x32_bf16 v[78:81], v[148:151], v[206:209], v[78:81]
	v_mfma_f32_16x16x32_bf16 v[74:77], v[158:161], v[206:209], v[74:77]
	v_mfma_f32_16x16x32_bf16 v[126:129], v[152:155], v[186:189], v[126:129]
	v_mfma_f32_16x16x32_bf16 v[122:125], v[162:165], v[186:189], v[122:125]
	v_mfma_f32_16x16x32_bf16 v[110:113], v[152:155], v[194:197], v[110:113]
	v_mfma_f32_16x16x32_bf16 v[106:109], v[162:165], v[194:197], v[106:109]
	v_mfma_f32_16x16x32_bf16 v[94:97], v[152:155], v[202:205], v[94:97]
	v_mfma_f32_16x16x32_bf16 v[90:93], v[162:165], v[202:205], v[90:93]
	v_mfma_f32_16x16x32_bf16 v[78:81], v[152:155], v[210:213], v[78:81]
	v_mfma_f32_16x16x32_bf16 v[74:77], v[162:165], v[210:213], v[74:77]
	s_setprio 0
	s_setprio 1
	v_mfma_f32_16x16x32_bf16 v[118:121], v[166:169], v[182:185], v[118:121]
	v_mfma_f32_16x16x32_bf16 v[114:117], v[174:177], v[182:185], v[114:117]
	v_mfma_f32_16x16x32_bf16 v[102:105], v[166:169], v[190:193], v[102:105]
	v_mfma_f32_16x16x32_bf16 v[98:101], v[174:177], v[190:193], v[98:101]
	v_mfma_f32_16x16x32_bf16 v[86:89], v[166:169], v[198:201], v[86:89]
	v_mfma_f32_16x16x32_bf16 v[82:85], v[174:177], v[198:201], v[82:85]
	v_mfma_f32_16x16x32_bf16 v[70:73], v[166:169], v[206:209], v[70:73]
	v_mfma_f32_16x16x32_bf16 v[66:69], v[174:177], v[206:209], v[66:69]
	v_mfma_f32_16x16x32_bf16 v[118:121], v[170:173], v[186:189], v[118:121]
	v_mfma_f32_16x16x32_bf16 v[114:117], v[178:181], v[186:189], v[114:117]
	v_mfma_f32_16x16x32_bf16 v[102:105], v[170:173], v[194:197], v[102:105]
	v_mfma_f32_16x16x32_bf16 v[98:101], v[178:181], v[194:197], v[98:101]
	v_mfma_f32_16x16x32_bf16 v[86:89], v[170:173], v[202:205], v[86:89]
	v_mfma_f32_16x16x32_bf16 v[82:85], v[178:181], v[202:205], v[82:85]
	v_mfma_f32_16x16x32_bf16 v[70:73], v[170:173], v[210:213], v[70:73]
	v_mfma_f32_16x16x32_bf16 v[66:69], v[178:181], v[210:213], v[66:69]
	s_setprio 0
	s_barrier
	s_mov_b32 m0, s40
	v_lshl_add_u64 v[214:215], v[214:215], 0, s[2:3]
	s_add_u32 s16, s16, 0x40080
	ds_read_b128 v[182:185], v145 offset:49152
	ds_read_b128 v[186:189], v145 offset:50176
	ds_read_b128 v[190:193], v145 offset:51200
	ds_read_b128 v[194:197], v145 offset:52224
	ds_read_b128 v[198:201], v145 offset:53248
	ds_read_b128 v[202:205], v145 offset:54272
	ds_read_b128 v[206:209], v145 offset:55296
	ds_read_b128 v[210:213], v145 offset:56320
	global_load_lds_dwordx4 v[214:215], off
	v_lshl_add_u64 v[214:215], v[216:217], 0, s[2:3]
	s_mov_b32 m0, s41
	s_addc_u32 s17, s17, 0
	global_load_lds_dwordx4 v[214:215], off
	s_mov_b32 m0, s42
	s_nop 0
	global_load_lds_dwordx4 v132, s[16:17]
	s_mov_b32 m0, s43
	s_nop 0
	global_load_lds_dwordx4 v136, s[16:17]
	v_lshl_add_u64 v[214:215], v[218:219], 0, s[2:3]
	s_mov_b32 m0, s22
	s_nop 0
	global_load_lds_dwordx4 v[214:215], off
	v_lshl_add_u64 v[214:215], v[220:221], 0, s[2:3]
	s_mov_b32 m0, s23
	s_nop 0
	global_load_lds_dwordx4 v[214:215], off
	s_waitcnt vmcnt(8)
	s_waitcnt lgkmcnt(0)
	s_barrier
	s_setprio 1
	s_waitcnt lgkmcnt(0)
	v_mfma_f32_16x16x32_bf16 v[62:65], v[148:151], v[182:185], v[62:65]
	v_mfma_f32_16x16x32_bf16 v[58:61], v[158:161], v[182:185], v[58:61]
	v_mfma_f32_16x16x32_bf16 v[46:49], v[148:151], v[190:193], v[46:49]
	v_mfma_f32_16x16x32_bf16 v[42:45], v[158:161], v[190:193], v[42:45]
	v_mfma_f32_16x16x32_bf16 v[30:33], v[148:151], v[198:201], v[30:33]
	v_mfma_f32_16x16x32_bf16 v[26:29], v[158:161], v[198:201], v[26:29]
	v_mfma_f32_16x16x32_bf16 v[14:17], v[148:151], v[206:209], v[14:17]
	v_mfma_f32_16x16x32_bf16 v[10:13], v[158:161], v[206:209], v[10:13]
	v_mfma_f32_16x16x32_bf16 v[62:65], v[152:155], v[186:189], v[62:65]
	v_mfma_f32_16x16x32_bf16 v[58:61], v[162:165], v[186:189], v[58:61]
	v_mfma_f32_16x16x32_bf16 v[46:49], v[152:155], v[194:197], v[46:49]
	v_mfma_f32_16x16x32_bf16 v[42:45], v[162:165], v[194:197], v[42:45]
	v_mfma_f32_16x16x32_bf16 v[30:33], v[152:155], v[202:205], v[30:33]
	v_mfma_f32_16x16x32_bf16 v[26:29], v[162:165], v[202:205], v[26:29]
	v_mfma_f32_16x16x32_bf16 v[14:17], v[152:155], v[210:213], v[14:17]
	v_mfma_f32_16x16x32_bf16 v[10:13], v[162:165], v[210:213], v[10:13]
	s_setprio 0
	s_setprio 1
	v_mfma_f32_16x16x32_bf16 v[54:57], v[166:169], v[182:185], v[54:57]
	v_mfma_f32_16x16x32_bf16 v[50:53], v[174:177], v[182:185], v[50:53]
	v_mfma_f32_16x16x32_bf16 v[38:41], v[166:169], v[190:193], v[38:41]
	v_mfma_f32_16x16x32_bf16 v[34:37], v[174:177], v[190:193], v[34:37]
	v_mfma_f32_16x16x32_bf16 v[22:25], v[166:169], v[198:201], v[22:25]
	v_mfma_f32_16x16x32_bf16 v[18:21], v[174:177], v[198:201], v[18:21]
	v_mfma_f32_16x16x32_bf16 v[6:9], v[166:169], v[206:209], v[6:9]
	v_mfma_f32_16x16x32_bf16 v[2:5], v[174:177], v[206:209], v[2:5]
	v_mfma_f32_16x16x32_bf16 v[54:57], v[170:173], v[186:189], v[54:57]
	v_mfma_f32_16x16x32_bf16 v[50:53], v[178:181], v[186:189], v[50:53]
	v_mfma_f32_16x16x32_bf16 v[38:41], v[170:173], v[194:197], v[38:41]
	v_mfma_f32_16x16x32_bf16 v[34:37], v[178:181], v[194:197], v[34:37]
	v_mfma_f32_16x16x32_bf16 v[22:25], v[170:173], v[202:205], v[22:25]
	v_mfma_f32_16x16x32_bf16 v[18:21], v[178:181], v[202:205], v[18:21]
	v_mfma_f32_16x16x32_bf16 v[6:9], v[170:173], v[210:213], v[6:9]
	v_mfma_f32_16x16x32_bf16 v[2:5], v[178:181], v[210:213], v[2:5]
	s_setprio 0
	s_barrier
	s_add_i32 s33, s33, 2
	s_add_u32 s10, s10, 0x100
	s_addc_u32 s11, s11, 0
	s_cmp_gt_u32 s33, 13
	s_cbranch_scc0 .LBB0_518
	s_cmpk_lt_u32 s14, 0x100
	s_cbranch_scc0 .LBB0_521
	s_barrier

.LBB0_1250:
	ds_read_b128 v[146:149], v140
	ds_read_b128 v[150:153], v140 offset:1024
	ds_read_b128 v[154:157], v140 offset:2048
	ds_read_b128 v[158:161], v140 offset:3072
	ds_read_b128 v[162:165], v141
	ds_read_b128 v[166:169], v141 offset:1024
	ds_read_b128 v[170:173], v141 offset:2048
	ds_read_b128 v[174:177], v141 offset:3072
	s_add_u32 s14, s10, s12
	s_addc_u32 s15, s11, s13
	s_add_u32 s14, s14, 0x11400100
	s_addc_u32 s15, s15, 0
	s_add_u32 s39, s1, s12
	s_addc_u32 s40, s26, s13
	s_cmpk_eq_i32 s12, 0x700
	s_cselect_b32 s17, s9, s15
	s_cselect_b32 s16, s8, s14
	s_cselect_b32 s15, s7, s40
	s_cselect_b32 s14, s6, s39
	s_mov_b32 m0, s28
	v_lshl_add_u64 v[210:211], v[134:135], 0, s[12:13]
	ds_read_b128 v[178:181], v142
	ds_read_b128 v[182:185], v142 offset:1024
	ds_read_b128 v[186:189], v142 offset:2048
	ds_read_b128 v[190:193], v142 offset:3072
	ds_read_b128 v[194:197], v142 offset:4096
	ds_read_b128 v[198:201], v142 offset:5120
	ds_read_b128 v[202:205], v142 offset:6144
	ds_read_b128 v[206:209], v142 offset:7168
	global_load_lds_dwordx4 v[210:211], off
	v_lshl_add_u64 v[210:211], v[136:137], 0, s[12:13]
	s_mov_b32 m0, s29
	s_nop 0
	global_load_lds_dwordx4 v[210:211], off
	s_waitcnt vmcnt(8)
	s_waitcnt lgkmcnt(0)
	s_barrier
	s_setprio 1
	s_waitcnt lgkmcnt(0)
	v_mfma_f32_16x16x32_bf16 v[126:129], v[146:149], v[178:181], v[126:129]
	v_mfma_f32_16x16x32_bf16 v[122:125], v[154:157], v[178:181], v[122:125]
	v_mfma_f32_16x16x32_bf16 v[118:121], v[146:149], v[186:189], v[118:121]
	v_mfma_f32_16x16x32_bf16 v[114:117], v[154:157], v[186:189], v[114:117]
	v_mfma_f32_16x16x32_bf16 v[106:109], v[146:149], v[194:197], v[106:109]
	v_mfma_f32_16x16x32_bf16 v[98:101], v[154:157], v[194:197], v[98:101]
	v_mfma_f32_16x16x32_bf16 v[82:85], v[146:149], v[202:205], v[82:85]
	v_mfma_f32_16x16x32_bf16 v[74:77], v[154:157], v[202:205], v[74:77]
	v_mfma_f32_16x16x32_bf16 v[126:129], v[150:153], v[182:185], v[126:129]
	v_mfma_f32_16x16x32_bf16 v[122:125], v[158:161], v[182:185], v[122:125]
	v_mfma_f32_16x16x32_bf16 v[118:121], v[150:153], v[190:193], v[118:121]
	v_mfma_f32_16x16x32_bf16 v[114:117], v[158:161], v[190:193], v[114:117]
	v_mfma_f32_16x16x32_bf16 v[106:109], v[150:153], v[198:201], v[106:109]
	v_mfma_f32_16x16x32_bf16 v[98:101], v[158:161], v[198:201], v[98:101]
	v_mfma_f32_16x16x32_bf16 v[82:85], v[150:153], v[206:209], v[82:85]
	v_mfma_f32_16x16x32_bf16 v[74:77], v[158:161], v[206:209], v[74:77]
	s_setprio 0
	s_setprio 1
	v_mfma_f32_16x16x32_bf16 v[110:113], v[162:165], v[178:181], v[110:113]
	v_mfma_f32_16x16x32_bf16 v[102:105], v[170:173], v[178:181], v[102:105]
	v_mfma_f32_16x16x32_bf16 v[94:97], v[162:165], v[186:189], v[94:97]
	v_mfma_f32_16x16x32_bf16 v[90:93], v[170:173], v[186:189], v[90:93]
	v_mfma_f32_16x16x32_bf16 v[86:89], v[162:165], v[194:197], v[86:89]
	v_mfma_f32_16x16x32_bf16 v[78:81], v[170:173], v[194:197], v[78:81]
	v_mfma_f32_16x16x32_bf16 v[70:73], v[162:165], v[202:205], v[70:73]
	v_mfma_f32_16x16x32_bf16 v[66:69], v[170:173], v[202:205], v[66:69]
	v_mfma_f32_16x16x32_bf16 v[110:113], v[166:169], v[182:185], v[110:113]
	v_mfma_f32_16x16x32_bf16 v[102:105], v[174:177], v[182:185], v[102:105]
	v_mfma_f32_16x16x32_bf16 v[94:97], v[166:169], v[190:193], v[94:97]
	v_mfma_f32_16x16x32_bf16 v[90:93], v[174:177], v[190:193], v[90:93]
	v_mfma_f32_16x16x32_bf16 v[86:89], v[166:169], v[198:201], v[86:89]
	v_mfma_f32_16x16x32_bf16 v[78:81], v[174:177], v[198:201], v[78:81]
	v_mfma_f32_16x16x32_bf16 v[70:73], v[166:169], v[206:209], v[70:73]
	v_mfma_f32_16x16x32_bf16 v[66:69], v[174:177], v[206:209], v[66:69]
	s_setprio 0
	s_barrier
	s_mov_b32 m0, s30
	v_lshl_add_u64 v[210:211], s[14:15], 0, v[130:131]
	s_add_u32 s40, s14, 0x40000
	ds_read_b128 v[178:181], v142 offset:16384
	ds_read_b128 v[182:185], v142 offset:17408
	ds_read_b128 v[186:189], v142 offset:18432
	ds_read_b128 v[190:193], v142 offset:19456
	ds_read_b128 v[194:197], v142 offset:20480
	ds_read_b128 v[198:201], v142 offset:21504
	ds_read_b128 v[202:205], v142 offset:22528
	ds_read_b128 v[206:209], v142 offset:23552
	global_load_lds_dwordx4 v130, s[14:15]
	v_lshl_add_u64 v[212:213], s[14:15], 0, v[132:133]
	s_mov_b32 m0, s31
	s_addc_u32 s41, s15, 0
	global_load_lds_dwordx4 v132, s[14:15]
	s_mov_b32 m0, s33
	v_lshl_add_u64 v[216:217], s[16:17], 0, v[132:133]
	global_load_lds_dwordx4 v130, s[40:41]
	s_mov_b32 m0, s34
	s_nop 0
	global_load_lds_dwordx4 v132, s[40:41]
	v_lshl_add_u64 v[214:215], s[16:17], 0, v[130:131]
	s_mov_b32 m0, s5
	s_nop 0
	global_load_lds_dwordx4 v130, s[16:17]
	s_mov_b32 m0, s21
	s_nop 0
	global_load_lds_dwordx4 v132, s[16:17]
	s_waitcnt vmcnt(8)
	s_waitcnt lgkmcnt(0)
	s_barrier
	s_setprio 1
	s_waitcnt lgkmcnt(0)
	v_mfma_f32_16x16x32_bf16 v[62:65], v[146:149], v[178:181], v[62:65]
	v_mfma_f32_16x16x32_bf16 v[58:61], v[154:157], v[178:181], v[58:61]
	v_mfma_f32_16x16x32_bf16 v[54:57], v[146:149], v[186:189], v[54:57]
	v_mfma_f32_16x16x32_bf16 v[50:53], v[154:157], v[186:189], v[50:53]
	v_mfma_f32_16x16x32_bf16 v[34:37], v[146:149], v[194:197], v[34:37]
	v_mfma_f32_16x16x32_bf16 v[26:29], v[154:157], v[194:197], v[26:29]
	v_mfma_f32_16x16x32_bf16 v[22:25], v[146:149], v[202:205], v[22:25]
	v_mfma_f32_16x16x32_bf16 v[10:13], v[154:157], v[202:205], v[10:13]
	v_mfma_f32_16x16x32_bf16 v[62:65], v[150:153], v[182:185], v[62:65]
	v_mfma_f32_16x16x32_bf16 v[58:61], v[158:161], v[182:185], v[58:61]
	v_mfma_f32_16x16x32_bf16 v[54:57], v[150:153], v[190:193], v[54:57]
	v_mfma_f32_16x16x32_bf16 v[50:53], v[158:161], v[190:193], v[50:53]
	v_mfma_f32_16x16x32_bf16 v[34:37], v[150:153], v[198:201], v[34:37]
	v_mfma_f32_16x16x32_bf16 v[26:29], v[158:161], v[198:201], v[26:29]
	v_mfma_f32_16x16x32_bf16 v[22:25], v[150:153], v[206:209], v[22:25]
	v_mfma_f32_16x16x32_bf16 v[10:13], v[158:161], v[206:209], v[10:13]
	s_setprio 0
	s_setprio 1
	v_mfma_f32_16x16x32_bf16 v[46:49], v[162:165], v[178:181], v[46:49]
	v_mfma_f32_16x16x32_bf16 v[42:45], v[170:173], v[178:181], v[42:45]
	v_mfma_f32_16x16x32_bf16 v[38:41], v[162:165], v[186:189], v[38:41]
	v_mfma_f32_16x16x32_bf16 v[30:33], v[170:173], v[186:189], v[30:33]
	v_mfma_f32_16x16x32_bf16 v[18:21], v[162:165], v[194:197], v[18:21]
	v_mfma_f32_16x16x32_bf16 v[14:17], v[170:173], v[194:197], v[14:17]
	v_mfma_f32_16x16x32_bf16 v[6:9], v[162:165], v[202:205], v[6:9]
	v_mfma_f32_16x16x32_bf16 v[2:5], v[170:173], v[202:205], v[2:5]
	v_mfma_f32_16x16x32_bf16 v[46:49], v[166:169], v[182:185], v[46:49]
	v_mfma_f32_16x16x32_bf16 v[42:45], v[174:177], v[182:185], v[42:45]
	v_mfma_f32_16x16x32_bf16 v[38:41], v[166:169], v[190:193], v[38:41]
	v_mfma_f32_16x16x32_bf16 v[30:33], v[174:177], v[190:193], v[30:33]
	v_mfma_f32_16x16x32_bf16 v[18:21], v[166:169], v[198:201], v[18:21]
	v_mfma_f32_16x16x32_bf16 v[14:17], v[174:177], v[198:201], v[14:17]
	v_mfma_f32_16x16x32_bf16 v[6:9], v[166:169], v[206:209], v[6:9]
	v_mfma_f32_16x16x32_bf16 v[2:5], v[174:177], v[206:209], v[2:5]
	s_setprio 0
	s_barrier
	ds_read_b128 v[146:149], v143
	ds_read_b128 v[150:153], v143 offset:1024
	ds_read_b128 v[154:157], v143 offset:2048
	ds_read_b128 v[158:161], v143 offset:3072
	ds_read_b128 v[162:165], v144
	ds_read_b128 v[166:169], v144 offset:1024
	ds_read_b128 v[170:173], v144 offset:2048
	ds_read_b128 v[174:177], v144 offset:3072
	s_add_u32 s16, s16, 0x40000
	s_addc_u32 s17, s17, 0
	s_mov_b32 m0, s22
	ds_read_b128 v[178:181], v142 offset:32768
	ds_read_b128 v[182:185], v142 offset:33792
	ds_read_b128 v[186:189], v142 offset:34816
	ds_read_b128 v[190:193], v142 offset:35840
	ds_read_b128 v[194:197], v142 offset:36864
	ds_read_b128 v[198:201], v142 offset:37888
	ds_read_b128 v[202:205], v142 offset:38912
	ds_read_b128 v[206:209], v142 offset:39936
	global_load_lds_dwordx4 v130, s[16:17]
	s_mov_b32 m0, s23
	s_nop 0
	global_load_lds_dwordx4 v132, s[16:17]
	s_waitcnt vmcnt(8)
	s_waitcnt lgkmcnt(0)
	s_barrier
	s_setprio 1
	s_waitcnt lgkmcnt(0)
	v_mfma_f32_16x16x32_bf16 v[126:129], v[146:149], v[178:181], v[126:129]
	v_mfma_f32_16x16x32_bf16 v[122:125], v[154:157], v[178:181], v[122:125]
	v_mfma_f32_16x16x32_bf16 v[118:121], v[146:149], v[186:189], v[118:121]
	v_mfma_f32_16x16x32_bf16 v[114:117], v[154:157], v[186:189], v[114:117]
	v_mfma_f32_16x16x32_bf16 v[106:109], v[146:149], v[194:197], v[106:109]
	v_mfma_f32_16x16x32_bf16 v[98:101], v[154:157], v[194:197], v[98:101]
	v_mfma_f32_16x16x32_bf16 v[82:85], v[146:149], v[202:205], v[82:85]
	v_mfma_f32_16x16x32_bf16 v[74:77], v[154:157], v[202:205], v[74:77]
	v_mfma_f32_16x16x32_bf16 v[126:129], v[150:153], v[182:185], v[126:129]
	v_mfma_f32_16x16x32_bf16 v[122:125], v[158:161], v[182:185], v[122:125]
	v_mfma_f32_16x16x32_bf16 v[118:121], v[150:153], v[190:193], v[118:121]
	v_mfma_f32_16x16x32_bf16 v[114:117], v[158:161], v[190:193], v[114:117]
	v_mfma_f32_16x16x32_bf16 v[106:109], v[150:153], v[198:201], v[106:109]
	v_mfma_f32_16x16x32_bf16 v[98:101], v[158:161], v[198:201], v[98:101]
	v_mfma_f32_16x16x32_bf16 v[82:85], v[150:153], v[206:209], v[82:85]
	v_mfma_f32_16x16x32_bf16 v[74:77], v[158:161], v[206:209], v[74:77]
	s_setprio 0
	s_setprio 1
	v_mfma_f32_16x16x32_bf16 v[110:113], v[162:165], v[178:181], v[110:113]
	v_mfma_f32_16x16x32_bf16 v[102:105], v[170:173], v[178:181], v[102:105]
	v_mfma_f32_16x16x32_bf16 v[94:97], v[162:165], v[186:189], v[94:97]
	v_mfma_f32_16x16x32_bf16 v[90:93], v[170:173], v[186:189], v[90:93]
	v_mfma_f32_16x16x32_bf16 v[86:89], v[162:165], v[194:197], v[86:89]
	v_mfma_f32_16x16x32_bf16 v[78:81], v[170:173], v[194:197], v[78:81]
	v_mfma_f32_16x16x32_bf16 v[70:73], v[162:165], v[202:205], v[70:73]
	v_mfma_f32_16x16x32_bf16 v[66:69], v[170:173], v[202:205], v[66:69]
	v_mfma_f32_16x16x32_bf16 v[110:113], v[166:169], v[182:185], v[110:113]
	v_mfma_f32_16x16x32_bf16 v[102:105], v[174:177], v[182:185], v[102:105]
	v_mfma_f32_16x16x32_bf16 v[94:97], v[166:169], v[190:193], v[94:97]
	v_mfma_f32_16x16x32_bf16 v[90:93], v[174:177], v[190:193], v[90:93]
	v_mfma_f32_16x16x32_bf16 v[86:89], v[166:169], v[198:201], v[86:89]
	v_mfma_f32_16x16x32_bf16 v[78:81], v[174:177], v[198:201], v[78:81]
	v_mfma_f32_16x16x32_bf16 v[70:73], v[166:169], v[206:209], v[70:73]
	v_mfma_f32_16x16x32_bf16 v[66:69], v[174:177], v[206:209], v[66:69]
	s_setprio 0
	s_barrier
	s_mov_b32 m0, s35
	v_lshl_add_u64 v[210:211], v[210:211], 0, s[2:3]
	s_add_u32 s14, s14, 0x40080
	ds_read_b128 v[178:181], v142 offset:49152
	ds_read_b128 v[182:185], v142 offset:50176
	ds_read_b128 v[186:189], v142 offset:51200
	ds_read_b128 v[190:193], v142 offset:52224
	ds_read_b128 v[194:197], v142 offset:53248
	ds_read_b128 v[198:201], v142 offset:54272
	ds_read_b128 v[202:205], v142 offset:55296
	ds_read_b128 v[206:209], v142 offset:56320
	global_load_lds_dwordx4 v[210:211], off
	v_lshl_add_u64 v[210:211], v[212:213], 0, s[2:3]
	s_mov_b32 m0, s36
	s_addc_u32 s15, s15, 0
	global_load_lds_dwordx4 v[210:211], off
	s_mov_b32 m0, s37
	s_nop 0
	global_load_lds_dwordx4 v130, s[14:15]
	s_mov_b32 m0, s38
	s_nop 0
	global_load_lds_dwordx4 v132, s[14:15]
	v_lshl_add_u64 v[210:211], v[214:215], 0, s[2:3]
	s_mov_b32 m0, s24
	s_nop 0
	global_load_lds_dwordx4 v[210:211], off
	v_lshl_add_u64 v[210:211], v[216:217], 0, s[2:3]
	s_mov_b32 m0, s25
	s_nop 0
	global_load_lds_dwordx4 v[210:211], off
	s_waitcnt vmcnt(8)
	s_waitcnt lgkmcnt(0)
	s_barrier
	s_setprio 1
	s_waitcnt lgkmcnt(0)
	v_mfma_f32_16x16x32_bf16 v[62:65], v[146:149], v[178:181], v[62:65]
	v_mfma_f32_16x16x32_bf16 v[58:61], v[154:157], v[178:181], v[58:61]
	v_mfma_f32_16x16x32_bf16 v[54:57], v[146:149], v[186:189], v[54:57]
	v_mfma_f32_16x16x32_bf16 v[50:53], v[154:157], v[186:189], v[50:53]
	v_mfma_f32_16x16x32_bf16 v[34:37], v[146:149], v[194:197], v[34:37]
	v_mfma_f32_16x16x32_bf16 v[26:29], v[154:157], v[194:197], v[26:29]
	v_mfma_f32_16x16x32_bf16 v[22:25], v[146:149], v[202:205], v[22:25]
	v_mfma_f32_16x16x32_bf16 v[10:13], v[154:157], v[202:205], v[10:13]
	v_mfma_f32_16x16x32_bf16 v[62:65], v[150:153], v[182:185], v[62:65]
	v_mfma_f32_16x16x32_bf16 v[58:61], v[158:161], v[182:185], v[58:61]
	v_mfma_f32_16x16x32_bf16 v[54:57], v[150:153], v[190:193], v[54:57]
	v_mfma_f32_16x16x32_bf16 v[50:53], v[158:161], v[190:193], v[50:53]
	v_mfma_f32_16x16x32_bf16 v[34:37], v[150:153], v[198:201], v[34:37]
	v_mfma_f32_16x16x32_bf16 v[26:29], v[158:161], v[198:201], v[26:29]
	v_mfma_f32_16x16x32_bf16 v[22:25], v[150:153], v[206:209], v[22:25]
	v_mfma_f32_16x16x32_bf16 v[10:13], v[158:161], v[206:209], v[10:13]
	s_setprio 0
	s_setprio 1
	v_mfma_f32_16x16x32_bf16 v[46:49], v[162:165], v[178:181], v[46:49]
	v_mfma_f32_16x16x32_bf16 v[42:45], v[170:173], v[178:181], v[42:45]
	v_mfma_f32_16x16x32_bf16 v[38:41], v[162:165], v[186:189], v[38:41]
	v_mfma_f32_16x16x32_bf16 v[30:33], v[170:173], v[186:189], v[30:33]
	v_mfma_f32_16x16x32_bf16 v[18:21], v[162:165], v[194:197], v[18:21]
	v_mfma_f32_16x16x32_bf16 v[14:17], v[170:173], v[194:197], v[14:17]
	v_mfma_f32_16x16x32_bf16 v[6:9], v[162:165], v[202:205], v[6:9]
	v_mfma_f32_16x16x32_bf16 v[2:5], v[170:173], v[202:205], v[2:5]
	v_mfma_f32_16x16x32_bf16 v[46:49], v[166:169], v[182:185], v[46:49]
	v_mfma_f32_16x16x32_bf16 v[42:45], v[174:177], v[182:185], v[42:45]
	v_mfma_f32_16x16x32_bf16 v[38:41], v[166:169], v[190:193], v[38:41]
	v_mfma_f32_16x16x32_bf16 v[30:33], v[174:177], v[190:193], v[30:33]
	v_mfma_f32_16x16x32_bf16 v[18:21], v[166:169], v[198:201], v[18:21]
	v_mfma_f32_16x16x32_bf16 v[14:17], v[174:177], v[198:201], v[14:17]
	v_mfma_f32_16x16x32_bf16 v[6:9], v[166:169], v[206:209], v[6:9]
	v_mfma_f32_16x16x32_bf16 v[2:5], v[174:177], v[206:209], v[2:5]
	s_setprio 0
	s_barrier
	s_add_i32 s27, s27, 2
	s_add_u32 s12, s12, 0x100
	s_addc_u32 s13, s13, 0
	s_cmp_gt_u32 s27, 13
	s_cbranch_scc0 .LBB0_1250
	s_cmpk_lt_u32 s19, 0x100
	s_cbranch_scc0 .LBB0_1253
	s_barrier

.LBB0_1381:
	ds_read_b128 v[138:141], v147
	ds_read_b128 v[150:153], v147 offset:1024
	ds_read_b128 v[154:157], v147 offset:2048
	ds_read_b128 v[158:161], v147 offset:3072
	ds_read_b128 v[162:165], v148
	ds_read_b128 v[166:169], v148 offset:1024
	ds_read_b128 v[170:173], v148 offset:2048
	ds_read_b128 v[174:177], v148 offset:3072
	s_add_u32 s24, s2, 0xfffc0080
	s_addc_u32 s25, s3, -1
	s_cmp_eq_u32 s53, 12
	s_cselect_b32 s27, s17, s25
	s_cselect_b32 s26, s49, s24
	s_cselect_b32 s25, s15, s52
	s_cselect_b32 s24, s50, s51
	s_add_i32 m0, s23, 0xc000
	ds_read_b128 v[178:181], v149
	ds_read_b128 v[182:185], v149 offset:1024
	ds_read_b128 v[186:189], v149 offset:2048
	ds_read_b128 v[190:193], v149 offset:3072
	ds_read_b128 v[194:197], v149 offset:4096
	ds_read_b128 v[198:201], v149 offset:5120
	ds_read_b128 v[202:205], v149 offset:6144
	ds_read_b128 v[206:209], v149 offset:7168
	global_load_lds_dwordx4 v132, s[2:3]
	s_add_i32 m0, s23, 0xe000
	s_nop 0
	global_load_lds_dwordx4 v134, s[2:3]
	s_waitcnt vmcnt(8)
	s_waitcnt lgkmcnt(0)
	s_barrier
	s_setprio 1
	s_waitcnt lgkmcnt(0)
	v_mfma_f32_16x16x32_bf16 v[124:127], v[138:141], v[178:181], v[124:127]
	v_mfma_f32_16x16x32_bf16 v[120:123], v[154:157], v[178:181], v[120:123]
	v_mfma_f32_16x16x32_bf16 v[116:119], v[138:141], v[186:189], v[116:119]
	v_mfma_f32_16x16x32_bf16 v[112:115], v[154:157], v[186:189], v[112:115]
	v_mfma_f32_16x16x32_bf16 v[104:107], v[138:141], v[194:197], v[104:107]
	v_mfma_f32_16x16x32_bf16 v[96:99], v[154:157], v[194:197], v[96:99]
	v_mfma_f32_16x16x32_bf16 v[88:91], v[138:141], v[202:205], v[88:91]
	v_mfma_f32_16x16x32_bf16 v[80:83], v[154:157], v[202:205], v[80:83]
	v_mfma_f32_16x16x32_bf16 v[124:127], v[150:153], v[182:185], v[124:127]
	v_mfma_f32_16x16x32_bf16 v[120:123], v[158:161], v[182:185], v[120:123]
	v_mfma_f32_16x16x32_bf16 v[116:119], v[150:153], v[190:193], v[116:119]
	v_mfma_f32_16x16x32_bf16 v[112:115], v[158:161], v[190:193], v[112:115]
	v_mfma_f32_16x16x32_bf16 v[104:107], v[150:153], v[198:201], v[104:107]
	v_mfma_f32_16x16x32_bf16 v[96:99], v[158:161], v[198:201], v[96:99]
	v_mfma_f32_16x16x32_bf16 v[88:91], v[150:153], v[206:209], v[88:91]
	v_mfma_f32_16x16x32_bf16 v[80:83], v[158:161], v[206:209], v[80:83]
	s_setprio 0
	s_setprio 1
	v_mfma_f32_16x16x32_bf16 v[108:111], v[162:165], v[178:181], v[108:111]
	v_mfma_f32_16x16x32_bf16 v[100:103], v[170:173], v[178:181], v[100:103]
	v_mfma_f32_16x16x32_bf16 v[92:95], v[162:165], v[186:189], v[92:95]
	v_mfma_f32_16x16x32_bf16 v[84:87], v[170:173], v[186:189], v[84:87]
	v_mfma_f32_16x16x32_bf16 v[76:79], v[162:165], v[194:197], v[76:79]
	v_mfma_f32_16x16x32_bf16 v[72:75], v[170:173], v[194:197], v[72:75]
	v_mfma_f32_16x16x32_bf16 v[68:71], v[162:165], v[202:205], v[68:71]
	v_mfma_f32_16x16x32_bf16 v[64:67], v[170:173], v[202:205], v[64:67]
	v_mfma_f32_16x16x32_bf16 v[108:111], v[166:169], v[182:185], v[108:111]
	v_mfma_f32_16x16x32_bf16 v[100:103], v[174:177], v[182:185], v[100:103]
	v_mfma_f32_16x16x32_bf16 v[92:95], v[166:169], v[190:193], v[92:95]
	v_mfma_f32_16x16x32_bf16 v[84:87], v[174:177], v[190:193], v[84:87]
	v_mfma_f32_16x16x32_bf16 v[76:79], v[166:169], v[198:201], v[76:79]
	v_mfma_f32_16x16x32_bf16 v[72:75], v[174:177], v[198:201], v[72:75]
	v_mfma_f32_16x16x32_bf16 v[68:71], v[166:169], v[206:209], v[68:71]
	v_mfma_f32_16x16x32_bf16 v[64:67], v[174:177], v[206:209], v[64:67]
	s_setprio 0
	s_barrier
	s_add_i32 s54, s4, s29
	s_mov_b32 m0, s54
	ds_read_b128 v[178:181], v149 offset:16384
	ds_read_b128 v[182:185], v149 offset:17408
	ds_read_b128 v[186:189], v149 offset:18432
	ds_read_b128 v[190:193], v149 offset:19456
	ds_read_b128 v[194:197], v149 offset:20480
	ds_read_b128 v[198:201], v149 offset:21504
	ds_read_b128 v[202:205], v149 offset:22528
	ds_read_b128 v[206:209], v149 offset:23552
	global_load_lds_dwordx4 v130, s[24:25]
	s_add_i32 m0, s54, 0x2000
	s_add_u32 s54, s24, 0x40000
	s_addc_u32 s55, s25, 0
	s_add_i32 s56, s41, s29
	global_load_lds_dwordx4 v128, s[24:25]
	s_mov_b32 m0, s56
	v_lshl_add_u64 v[214:215], s[26:27], 0, v[128:129]
	global_load_lds_dwordx4 v130, s[54:55]
	s_add_i32 m0, s56, 0x2000
	s_nop 0
	global_load_lds_dwordx4 v128, s[54:55]
	v_lshl_add_u64 v[212:213], s[26:27], 0, v[130:131]
	s_mov_b32 m0, s23
	s_nop 0
	global_load_lds_dwordx4 v130, s[26:27]
	s_mov_b32 m0, s34
	s_nop 0
	global_load_lds_dwordx4 v128, s[26:27]
	s_waitcnt vmcnt(8)
	s_waitcnt lgkmcnt(0)
	s_barrier
	s_setprio 1
	s_waitcnt lgkmcnt(0)
	v_mfma_f32_16x16x32_bf16 v[60:63], v[138:141], v[178:181], v[60:63]
	v_mfma_f32_16x16x32_bf16 v[56:59], v[154:157], v[178:181], v[56:59]
	v_mfma_f32_16x16x32_bf16 v[52:55], v[138:141], v[186:189], v[52:55]
	v_mfma_f32_16x16x32_bf16 v[48:51], v[154:157], v[186:189], v[48:51]
	v_mfma_f32_16x16x32_bf16 v[44:47], v[138:141], v[194:197], v[44:47]
	v_mfma_f32_16x16x32_bf16 v[32:35], v[154:157], v[194:197], v[32:35]
	v_mfma_f32_16x16x32_bf16 v[20:23], v[138:141], v[202:205], v[20:23]
	v_mfma_f32_16x16x32_bf16 v[8:11], v[154:157], v[202:205], v[8:11]
	v_mfma_f32_16x16x32_bf16 v[60:63], v[150:153], v[182:185], v[60:63]
	v_mfma_f32_16x16x32_bf16 v[56:59], v[158:161], v[182:185], v[56:59]
	v_mfma_f32_16x16x32_bf16 v[52:55], v[150:153], v[190:193], v[52:55]
	v_mfma_f32_16x16x32_bf16 v[48:51], v[158:161], v[190:193], v[48:51]
	v_mfma_f32_16x16x32_bf16 v[44:47], v[150:153], v[198:201], v[44:47]
	v_mfma_f32_16x16x32_bf16 v[32:35], v[158:161], v[198:201], v[32:35]
	v_mfma_f32_16x16x32_bf16 v[20:23], v[150:153], v[206:209], v[20:23]
	v_mfma_f32_16x16x32_bf16 v[8:11], v[158:161], v[206:209], v[8:11]
	s_setprio 0
	s_setprio 1
	v_mfma_f32_16x16x32_bf16 v[40:43], v[162:165], v[178:181], v[40:43]
	v_mfma_f32_16x16x32_bf16 v[36:39], v[170:173], v[178:181], v[36:39]
	v_mfma_f32_16x16x32_bf16 v[28:31], v[162:165], v[186:189], v[28:31]
	v_mfma_f32_16x16x32_bf16 v[24:27], v[170:173], v[186:189], v[24:27]
	v_mfma_f32_16x16x32_bf16 v[16:19], v[162:165], v[194:197], v[16:19]
	v_mfma_f32_16x16x32_bf16 v[12:15], v[170:173], v[194:197], v[12:15]
	v_mfma_f32_16x16x32_bf16 v[4:7], v[162:165], v[202:205], v[4:7]
	v_mfma_f32_16x16x32_bf16 v[0:3], v[170:173], v[202:205], v[0:3]
	v_mfma_f32_16x16x32_bf16 v[40:43], v[166:169], v[182:185], v[40:43]
	v_mfma_f32_16x16x32_bf16 v[36:39], v[174:177], v[182:185], v[36:39]
	v_mfma_f32_16x16x32_bf16 v[28:31], v[166:169], v[190:193], v[28:31]
	v_mfma_f32_16x16x32_bf16 v[24:27], v[174:177], v[190:193], v[24:27]
	v_mfma_f32_16x16x32_bf16 v[16:19], v[166:169], v[198:201], v[16:19]
	v_mfma_f32_16x16x32_bf16 v[12:15], v[174:177], v[198:201], v[12:15]
	v_mfma_f32_16x16x32_bf16 v[4:7], v[166:169], v[206:209], v[4:7]
	v_mfma_f32_16x16x32_bf16 v[0:3], v[174:177], v[206:209], v[0:3]
	s_setprio 0
	s_barrier
	s_add_i32 s54, 0, 0x18000
	s_add_i32 s55, 0, 0x1c000
	v_add_u32_e32 v158, s54, v145
	v_add_u32_e32 v174, s55, v145
	ds_read_b128 v[138:141], v158
	ds_read_b128 v[150:153], v158 offset:1024
	ds_read_b128 v[154:157], v158 offset:2048
	ds_read_b128 v[158:161], v158 offset:3072
	ds_read_b128 v[162:165], v174
	ds_read_b128 v[166:169], v174 offset:1024
	ds_read_b128 v[170:173], v174 offset:2048
	ds_read_b128 v[174:177], v174 offset:3072
	s_add_u32 s26, s26, 0x40000
	s_addc_u32 s27, s27, 0
	s_mov_b32 m0, s35
	ds_read_b128 v[178:181], v149 offset:32768
	ds_read_b128 v[182:185], v149 offset:33792
	ds_read_b128 v[186:189], v149 offset:34816
	ds_read_b128 v[190:193], v149 offset:35840
	ds_read_b128 v[194:197], v149 offset:36864
	ds_read_b128 v[198:201], v149 offset:37888
	ds_read_b128 v[202:205], v149 offset:38912
	ds_read_b128 v[206:209], v149 offset:39936
	global_load_lds_dwordx4 v130, s[26:27]
	s_mov_b32 m0, s36
	s_nop 0
	global_load_lds_dwordx4 v128, s[26:27]
	s_waitcnt vmcnt(8)
	s_waitcnt lgkmcnt(0)
	s_barrier
	s_setprio 1
	s_waitcnt lgkmcnt(0)
	v_mfma_f32_16x16x32_bf16 v[124:127], v[138:141], v[178:181], v[124:127]
	v_mfma_f32_16x16x32_bf16 v[120:123], v[154:157], v[178:181], v[120:123]
	v_mfma_f32_16x16x32_bf16 v[116:119], v[138:141], v[186:189], v[116:119]
	v_mfma_f32_16x16x32_bf16 v[112:115], v[154:157], v[186:189], v[112:115]
	v_mfma_f32_16x16x32_bf16 v[104:107], v[138:141], v[194:197], v[104:107]
	v_mfma_f32_16x16x32_bf16 v[96:99], v[154:157], v[194:197], v[96:99]
	v_mfma_f32_16x16x32_bf16 v[88:91], v[138:141], v[202:205], v[88:91]
	v_mfma_f32_16x16x32_bf16 v[80:83], v[154:157], v[202:205], v[80:83]
	v_mfma_f32_16x16x32_bf16 v[124:127], v[150:153], v[182:185], v[124:127]
	v_mfma_f32_16x16x32_bf16 v[120:123], v[158:161], v[182:185], v[120:123]
	v_mfma_f32_16x16x32_bf16 v[116:119], v[150:153], v[190:193], v[116:119]
	v_mfma_f32_16x16x32_bf16 v[112:115], v[158:161], v[190:193], v[112:115]
	v_mfma_f32_16x16x32_bf16 v[104:107], v[150:153], v[198:201], v[104:107]
	v_mfma_f32_16x16x32_bf16 v[96:99], v[158:161], v[198:201], v[96:99]
	v_mfma_f32_16x16x32_bf16 v[88:91], v[150:153], v[206:209], v[88:91]
	v_mfma_f32_16x16x32_bf16 v[80:83], v[158:161], v[206:209], v[80:83]
	s_setprio 0
	s_setprio 1
	v_mfma_f32_16x16x32_bf16 v[108:111], v[162:165], v[178:181], v[108:111]
	v_mfma_f32_16x16x32_bf16 v[100:103], v[170:173], v[178:181], v[100:103]
	v_mfma_f32_16x16x32_bf16 v[92:95], v[162:165], v[186:189], v[92:95]
	v_mfma_f32_16x16x32_bf16 v[84:87], v[170:173], v[186:189], v[84:87]
	v_mfma_f32_16x16x32_bf16 v[76:79], v[162:165], v[194:197], v[76:79]
	v_mfma_f32_16x16x32_bf16 v[72:75], v[170:173], v[194:197], v[72:75]
	v_mfma_f32_16x16x32_bf16 v[68:71], v[162:165], v[202:205], v[68:71]
	v_mfma_f32_16x16x32_bf16 v[64:67], v[170:173], v[202:205], v[64:67]
	v_mfma_f32_16x16x32_bf16 v[108:111], v[166:169], v[182:185], v[108:111]
	v_mfma_f32_16x16x32_bf16 v[100:103], v[174:177], v[182:185], v[100:103]
	v_mfma_f32_16x16x32_bf16 v[92:95], v[166:169], v[190:193], v[92:95]
	v_mfma_f32_16x16x32_bf16 v[84:87], v[174:177], v[190:193], v[84:87]
	v_mfma_f32_16x16x32_bf16 v[76:79], v[166:169], v[198:201], v[76:79]
	v_mfma_f32_16x16x32_bf16 v[72:75], v[174:177], v[198:201], v[72:75]
	v_mfma_f32_16x16x32_bf16 v[68:71], v[166:169], v[206:209], v[68:71]
	v_mfma_f32_16x16x32_bf16 v[64:67], v[174:177], v[206:209], v[64:67]
	s_setprio 0
	s_barrier
	s_add_i32 s26, s54, s29
	s_add_i32 m0, s26, 0xffffff80
	ds_read_b128 v[178:181], v149 offset:49152
	ds_read_b128 v[182:185], v149 offset:50176
	ds_read_b128 v[186:189], v149 offset:51200
	ds_read_b128 v[190:193], v149 offset:52224
	ds_read_b128 v[194:197], v149 offset:53248
	ds_read_b128 v[198:201], v149 offset:54272
	ds_read_b128 v[202:205], v149 offset:55296
	ds_read_b128 v[206:209], v149 offset:56320
	global_load_lds_dwordx4 v130, s[24:25] offset:128
	s_add_i32 m0, s26, 0x1f80
	s_add_i32 s26, s55, s29
	global_load_lds_dwordx4 v128, s[24:25] offset:128
	s_add_u32 s24, s24, 0x40080
	s_addc_u32 s25, s25, 0
	s_mov_b32 m0, s26
	s_nop 0
	global_load_lds_dwordx4 v130, s[24:25]
	s_add_i32 m0, s26, 0x2000
	s_nop 0
	global_load_lds_dwordx4 v128, s[24:25]
	v_lshl_add_u64 v[142:143], v[212:213], 0, s[8:9]
	s_mov_b32 m0, s38
	s_nop 0
	global_load_lds_dwordx4 v[142:143], off
	v_lshl_add_u64 v[142:143], v[214:215], 0, s[8:9]
	s_mov_b32 m0, s39
	s_nop 0
	global_load_lds_dwordx4 v[142:143], off
	s_waitcnt vmcnt(8)
	s_waitcnt lgkmcnt(0)
	s_barrier
	s_setprio 1
	s_waitcnt lgkmcnt(0)
	v_mfma_f32_16x16x32_bf16 v[60:63], v[138:141], v[178:181], v[60:63]
	v_mfma_f32_16x16x32_bf16 v[56:59], v[154:157], v[178:181], v[56:59]
	v_mfma_f32_16x16x32_bf16 v[52:55], v[138:141], v[186:189], v[52:55]
	v_mfma_f32_16x16x32_bf16 v[48:51], v[154:157], v[186:189], v[48:51]
	v_mfma_f32_16x16x32_bf16 v[44:47], v[138:141], v[194:197], v[44:47]
	v_mfma_f32_16x16x32_bf16 v[32:35], v[154:157], v[194:197], v[32:35]
	v_mfma_f32_16x16x32_bf16 v[20:23], v[138:141], v[202:205], v[20:23]
	v_mfma_f32_16x16x32_bf16 v[8:11], v[154:157], v[202:205], v[8:11]
	v_mfma_f32_16x16x32_bf16 v[60:63], v[150:153], v[182:185], v[60:63]
	v_mfma_f32_16x16x32_bf16 v[56:59], v[158:161], v[182:185], v[56:59]
	v_mfma_f32_16x16x32_bf16 v[52:55], v[150:153], v[190:193], v[52:55]
	v_mfma_f32_16x16x32_bf16 v[48:51], v[158:161], v[190:193], v[48:51]
	v_mfma_f32_16x16x32_bf16 v[44:47], v[150:153], v[198:201], v[44:47]
	v_mfma_f32_16x16x32_bf16 v[32:35], v[158:161], v[198:201], v[32:35]
	v_mfma_f32_16x16x32_bf16 v[20:23], v[150:153], v[206:209], v[20:23]
	v_mfma_f32_16x16x32_bf16 v[8:11], v[158:161], v[206:209], v[8:11]
	s_setprio 0
	s_setprio 1
	v_mfma_f32_16x16x32_bf16 v[40:43], v[162:165], v[178:181], v[40:43]
	v_mfma_f32_16x16x32_bf16 v[36:39], v[170:173], v[178:181], v[36:39]
	v_mfma_f32_16x16x32_bf16 v[28:31], v[162:165], v[186:189], v[28:31]
	v_mfma_f32_16x16x32_bf16 v[24:27], v[170:173], v[186:189], v[24:27]
	v_mfma_f32_16x16x32_bf16 v[16:19], v[162:165], v[194:197], v[16:19]
	v_mfma_f32_16x16x32_bf16 v[12:15], v[170:173], v[194:197], v[12:15]
	v_mfma_f32_16x16x32_bf16 v[4:7], v[162:165], v[202:205], v[4:7]
	v_mfma_f32_16x16x32_bf16 v[0:3], v[170:173], v[202:205], v[0:3]
	v_mfma_f32_16x16x32_bf16 v[40:43], v[166:169], v[182:185], v[40:43]
	v_mfma_f32_16x16x32_bf16 v[36:39], v[174:177], v[182:185], v[36:39]
	v_mfma_f32_16x16x32_bf16 v[28:31], v[166:169], v[190:193], v[28:31]
	v_mfma_f32_16x16x32_bf16 v[24:27], v[174:177], v[190:193], v[24:27]
	v_mfma_f32_16x16x32_bf16 v[16:19], v[166:169], v[198:201], v[16:19]
	v_mfma_f32_16x16x32_bf16 v[12:15], v[174:177], v[198:201], v[12:15]
	v_mfma_f32_16x16x32_bf16 v[4:7], v[166:169], v[206:209], v[4:7]
	v_mfma_f32_16x16x32_bf16 v[0:3], v[174:177], v[206:209], v[0:3]
	s_setprio 0
	s_barrier
	s_add_i32 s53, s53, 2
	s_add_u32 s2, s2, 0x100
	s_addc_u32 s3, s3, 0
	s_add_u32 s51, s51, 0x100
	s_addc_u32 s52, s52, 0
	s_cmp_gt_u32 s53, 13
	s_cbranch_scc0 .LBB0_1381
	s_and_b64 vcc, exec, s[10:11]
	s_cbranch_vccz .LBB0_1384
	s_barrier
